# phase 2 blocks (gMLP / LRU+gather / memory attention) run in a rotated order per workgroup group (3 groups) so bandwidth-bound and compute-bound blocks overlap across the chip
# speedup vs baseline: 1.0110x; 1.0032x over previous
; #define LAS __attribute__((address_space(3)))
; __global__ void __launch_bounds__(512, 2) fwd_megakernel(Params PK) {
;     ...
;         } else if (ph == 2) {
;             for (int u = bid; u < 256; u += G) gmlp_unit(lds, P, l, u);
;             { int cur_n = -1;
;                 for (int u = bid; u < 1024; u += G) { const int n = u & 7;
;                     if (n != cur_n) { __syncthreads(); const bf16_t* WAT = (const bf16_t*)(ws + WS_WAT); LAS bf16_t* wl = (LAS bf16_t*)(lds + 34816);
;                         for (int q = tid; q < 2 * 128 * 16; q += 512) { const int mat = q >> 11, r = (q >> 4) & 127, sg = q & 15;
;                             *(LAS u32x4*)(wl + (mat * 128 + r) * 136 + sg * 8) = *(const u32x4*)(WAT + ((size_t)(mat * 8 + n) * 128 + r) * 128 + sg * 8); }
;                         cur_n = n; __syncthreads(); }
;                     lru_a_unit(lds, P, l, u); } }
;             { bf16_t* A0 = (bf16_t*)(ws + WS_A0);
;                 for (size_t idx = gtid; idx < (size_t)2 * 4096 * 256; idx += gstride) { const int ch = (int)(idx & 255), row = (int)((idx >> 8) & 4095), kv = (int)(idx >> 20);
;                     const int j = ch >> 3, d8 = (ch & 7) * 8, bh = row >> 8, n = row & 255, b = bh >> 2, hkv = bh & 3;
;                     u32x4 v = (u32x4){0u, 0u, 0u, 0u};
;                     if (n < 255) v = *(const u32x4*)(Hh + ((size_t)b * SEQ + 16 * n + j) * LDH + (kv ? C_VC : C_KC) + hkv * 64 + d8);
;                     *(u32x4*)(A0 + ((size_t)kv * 4096 + row) * 2048 + j * 64 + d8) = v; } }
;             __syncthreads();
;             for (int u = bid; u < 512; u += G) memattn_unit(lds, P, u);
.LBB0_787:
	s_and_b64 vcc, exec, s[0:1]
	s_cbranch_vccz .LBB0_859
	s_lshr_b32 s47, s2, 3
	s_mul_i32 s46, s47, 11
	s_lshr_b32 s46, s46, 5
	s_mul_i32 s46, s46, 3
	s_sub_u32 s47, s47, s46
	s_movk_i32 s46, 0xe4
	s_cmp_eq_u32 s47, 1
	s_cselect_b32 s46, 0xc9, s46
	s_cmp_eq_u32 s47, 2
	s_cselect_b32 s46, 0xd2, s46
	s_branch .Lp2_first
.Lp2_disp:
	s_lshr_b32 s46, s46, 2
.Lp2_first:
	s_and_b32 s47, s46, 3
	s_cmp_eq_u32 s47, 0
	s_cbranch_scc1 .Lp2_G
	s_cmp_eq_u32 s47, 1
	s_cbranch_scc1 .Lp2_L
	s_cmp_eq_u32 s47, 2
	s_cbranch_scc1 .Lp2_M
	s_branch .LBB0_859

; __global__ void __launch_bounds__(512, 2) fwd_megakernel(Params PK) {
;     ...
;             for (int u = bid; u < 256; u += G) gmlp_unit(lds, P, l, u);
;             { int cur_n = -1;
;                 for (int u = bid; u < 1024; u += G) { const int n = u & 7;
.LBB0_803:
	v_readlane_b32 s0, v255, 45
	v_readlane_b32 s1, v255, 46
	s_branch .LBB0_862
.LBB0_804:
	s_branch .Lp2_disp

; #define LAS __attribute__((address_space(3)))
; __device__ __forceinline__ int opaque_tid() { int t = threadIdx.x; asm volatile("" : "+v"(t)); return t; }
; __device__ __forceinline__ void memattn_unit(LAS unsigned char* lds, const Ctx& P, int unit) {
;     const bf16_t* H = (const bf16_t*)(P.ws + WS_H); const bf16_t* MKV = (const bf16_t*)(P.ws + WS_MKV); bf16_t* O = (bf16_t*)(P.ws + WS_O) + (size_t)3 * MT * DBR;
;     LAS bf16_t* Ks = (LAS bf16_t*)lds; LAS bf16_t* Vt = (LAS bf16_t*)(lds + 64 * 264 * 2);
;     const int tb = unit & 31, head = (unit >> 5) & 3, b = unit >> 7;
;     const int tid = opaque_tid(), wid = tid >> 6, lane = tid & 63, c = lane & 15, i = lane >> 4;
;     const size_t tok = (size_t)b * SEQ + tb * 128 + wid * 16 + c;
; __global__ void __launch_bounds__(512, 2) fwd_megakernel(Params PK) {
;     ...
;             { bf16_t* A0 = (bf16_t*)(ws + WS_A0);
;                 for (size_t idx = gtid; idx < (size_t)2 * 4096 * 256; idx += gstride) { const int ch = (int)(idx & 255), row = (int)((idx >> 8) & 4095), kv = (int)(idx >> 20);
;                     const int j = ch >> 3, d8 = (ch & 7) * 8, bh = row >> 8, n = row & 255, b = bh >> 2, hkv = bh & 3;
;                     u32x4 v = (u32x4){0u, 0u, 0u, 0u};
;                     if (n < 255) v = *(const u32x4*)(Hh + ((size_t)b * SEQ + 16 * n + j) * LDH + (kv ? C_VC : C_KC) + hkv * 64 + d8);
;                     *(u32x4*)(A0 + ((size_t)kv * 4096 + row) * 2048 + j * 64 + d8) = v; } }
;             __syncthreads();
;             for (int u = bid; u < 512; u += G) memattn_unit(lds, P, u);
.LBB0_851:
	s_or_b64 exec, exec, s[0:1]
	s_branch .Lp2_disp
.Lp2_M:
	v_readlane_b32 s0, v253, 11
	v_readlane_b32 s1, v253, 12
	s_andn2_b64 vcc, exec, s[0:1]
	s_barrier
	s_cbranch_vccnz .Lmem_done
	v_and_b32_e32 v219, 15, v234
	v_bfe_u32 v218, v234, 4, 2
	v_mul_u32_u24_e32 v202, 528, v219
	v_lshl_add_u32 v202, v218, 4, v202
	v_add_u32_e32 v203, 67584, v202
	v_lshrrev_b32_e32 v122, 2, v219
	v_lshl_add_u32 v122, v218, 2, v122
	v_mul_u32_u24_e32 v122, 528, v122
	v_and_b32_e32 v123, 3, v219
	v_lshl_add_u32 v204, v123, 3, v122
	v_add_u32_e32 v205, 67584, v204
	v_lshrrev_b32_e32 v122, 5, v234
	v_and_b32_e32 v123, 31, v234
	v_mul_u32_u24_e32 v206, 528, v122
	v_lshl_add_u32 v206, v123, 4, v206
	v_add_u32_e32 v216, 67584, v206
	v_lshlrev_b32_e32 v209, 12, v122
	v_lshl_add_u32 v209, v123, 4, v209
	v_lshrrev_b32_e32 v122, 6, v234
	v_lshl_add_u32 v217, v122, 4, v219
	s_mov_b32 s7, s2

; #define LAS __attribute__((address_space(3)))
; __device__ __forceinline__ f32x4 mfma16(bf16x8 a, bf16x8 b, f32x4 c) { return __builtin_amdgcn_mfma_f32_16x16x32_bf16(a, b, c, 0, 0, 0); }
; template <int D, class SF>
; __device__ __forceinline__ void attn_step(const bf16x8 (&qf)[D / 32], const LAS bf16_t* Ks, const LAS bf16_t* Vt, f32x4 (&o)[D / 16], float& m, float& lsum, float& alpha_out, bf16x8& pf0_out, bf16x8& pf1_out, const int lane, SF sf) {
;     ...
; #pragma unroll
;     for (int dt = 0; dt < D / 16; ++dt) {
;         const LAS bf16_t* vp = Vt + (16 * dt + c) * 72 + 4 * i;
;         union { u32x4 u; bf16x8 b; } vf0, vf1; const u32x2 a0 = *(const LAS u32x2*)vp, a1 = *(const LAS u32x2*)(vp + 16), b0 = *(const LAS u32x2*)(vp + 32), b1 = *(const LAS u32x2*)(vp + 48);
;         vf0.u.x = a0.x; vf0.u.y = a0.y; vf0.u.z = a1.x; vf0.u.w = a1.y; vf1.u.x = b0.x; vf1.u.y = b0.y; vf1.u.z = b1.x; vf1.u.w = b1.y;
;         o[dt] = mfma16(vf0.b, pk0.b, o[dt]); o[dt] = mfma16(vf1.b, pk1.b, o[dt]);
;     }
; __device__ __forceinline__ void memattn_unit(LAS unsigned char* lds, const Ctx& P, int unit) {
;     ...
;     const float inv = 1.0f / fmaxf(lsum, 1e-30f);
; #pragma unroll
;     for (int dt = 0; dt < 16; ++dt) { const int d0 = 16 * dt + 4 * i; const u32x2 g = *(const u32x2*)(H + tok * LDH + C_GM + head * 256 + d0);
.Lmem_nosc_4:
	s_waitcnt lgkmcnt(0)
	s_nop 1
	v_mfma_f32_16x16x32_bf16 v[34:37], v[130:133], v[114:117], v[34:37]
	v_mfma_f32_16x16x32_bf16 v[38:41], v[138:141], v[114:117], v[38:41]
	v_mfma_f32_16x16x32_bf16 v[42:45], v[146:149], v[114:117], v[42:45]
	v_mfma_f32_16x16x32_bf16 v[46:49], v[154:157], v[114:117], v[46:49]
	v_mfma_f32_16x16x32_bf16 v[34:37], v[134:137], v[118:121], v[34:37]
	v_mfma_f32_16x16x32_bf16 v[38:41], v[142:145], v[118:121], v[38:41]
	v_mfma_f32_16x16x32_bf16 v[42:45], v[150:153], v[118:121], v[42:45]
	v_mfma_f32_16x16x32_bf16 v[46:49], v[158:161], v[118:121], v[46:49]
	ds_read_b64_tr_b16 v[130:131], v205 offset:34048
	ds_read_b64_tr_b16 v[132:133], v205 offset:42496
	ds_read_b64_tr_b16 v[134:135], v205 offset:50944
	ds_read_b64_tr_b16 v[136:137], v205 offset:59392
	ds_read_b64_tr_b16 v[138:139], v205 offset:34080
	ds_read_b64_tr_b16 v[140:141], v205 offset:42528
	ds_read_b64_tr_b16 v[142:143], v205 offset:50976
	ds_read_b64_tr_b16 v[144:145], v205 offset:59424
	ds_read_b64_tr_b16 v[146:147], v205 offset:34112
	ds_read_b64_tr_b16 v[148:149], v205 offset:42560
	ds_read_b64_tr_b16 v[150:151], v205 offset:51008
	ds_read_b64_tr_b16 v[152:153], v205 offset:59456
	ds_read_b64_tr_b16 v[154:155], v205 offset:34144
	ds_read_b64_tr_b16 v[156:157], v205 offset:42592
	ds_read_b64_tr_b16 v[158:159], v205 offset:51040
	ds_read_b64_tr_b16 v[160:161], v205 offset:59488
	s_waitcnt lgkmcnt(15)
	v_mfma_f32_16x16x32_bf16 v[50:53], v[170:173], v[114:117], v[50:53]
	v_mfma_f32_16x16x32_bf16 v[54:57], v[178:181], v[114:117], v[54:57]
	v_mfma_f32_16x16x32_bf16 v[58:61], v[186:189], v[114:117], v[58:61]
	v_mfma_f32_16x16x32_bf16 v[62:65], v[194:197], v[114:117], v[62:65]
	v_mfma_f32_16x16x32_bf16 v[50:53], v[174:177], v[118:121], v[50:53]
	v_mfma_f32_16x16x32_bf16 v[54:57], v[182:185], v[118:121], v[54:57]
	v_mfma_f32_16x16x32_bf16 v[58:61], v[190:193], v[118:121], v[58:61]
	v_mfma_f32_16x16x32_bf16 v[62:65], v[198:201], v[118:121], v[62:65]
	ds_read_b64_tr_b16 v[170:171], v205 offset:34176
	ds_read_b64_tr_b16 v[172:173], v205 offset:42624
	ds_read_b64_tr_b16 v[174:175], v205 offset:51072
	ds_read_b64_tr_b16 v[176:177], v205 offset:59520
	ds_read_b64_tr_b16 v[178:179], v205 offset:34208
	ds_read_b64_tr_b16 v[180:181], v205 offset:42656
	ds_read_b64_tr_b16 v[182:183], v205 offset:51104
	ds_read_b64_tr_b16 v[184:185], v205 offset:59552
	ds_read_b64_tr_b16 v[186:187], v205 offset:34240
	ds_read_b64_tr_b16 v[188:189], v205 offset:42688
	ds_read_b64_tr_b16 v[190:191], v205 offset:51136
	ds_read_b64_tr_b16 v[192:193], v205 offset:59584
	ds_read_b64_tr_b16 v[194:195], v205 offset:34272
	ds_read_b64_tr_b16 v[196:197], v205 offset:42720
	ds_read_b64_tr_b16 v[198:199], v205 offset:51168
	ds_read_b64_tr_b16 v[200:201], v205 offset:59616
	s_waitcnt lgkmcnt(15)
	v_mfma_f32_16x16x32_bf16 v[66:69], v[130:133], v[114:117], v[66:69]
	v_mfma_f32_16x16x32_bf16 v[70:73], v[138:141], v[114:117], v[70:73]
	v_mfma_f32_16x16x32_bf16 v[74:77], v[146:149], v[114:117], v[74:77]
	v_mfma_f32_16x16x32_bf16 v[78:81], v[154:157], v[114:117], v[78:81]
	v_mfma_f32_16x16x32_bf16 v[66:69], v[134:137], v[118:121], v[66:69]
	v_mfma_f32_16x16x32_bf16 v[70:73], v[142:145], v[118:121], v[70:73]
	v_mfma_f32_16x16x32_bf16 v[74:77], v[150:153], v[118:121], v[74:77]
	v_mfma_f32_16x16x32_bf16 v[78:81], v[158:161], v[118:121], v[78:81]
	s_waitcnt lgkmcnt(0)
	v_mfma_f32_16x16x32_bf16 v[82:85], v[170:173], v[114:117], v[82:85]
	v_mfma_f32_16x16x32_bf16 v[86:89], v[178:181], v[114:117], v[86:89]
	v_mfma_f32_16x16x32_bf16 v[90:93], v[186:189], v[114:117], v[90:93]
	v_mfma_f32_16x16x32_bf16 v[94:97], v[194:197], v[114:117], v[94:97]
	v_mfma_f32_16x16x32_bf16 v[82:85], v[174:177], v[118:121], v[82:85]
	v_mfma_f32_16x16x32_bf16 v[86:89], v[182:185], v[118:121], v[86:89]
	v_mfma_f32_16x16x32_bf16 v[90:93], v[190:193], v[118:121], v[90:93]
	v_mfma_f32_16x16x32_bf16 v[94:97], v[198:201], v[118:121], v[94:97]
	global_load_dwordx2 v[130:131], v[214:215], off
	global_load_dwordx2 v[132:133], v[214:215], off offset:32
	global_load_dwordx2 v[134:135], v[214:215], off offset:64
	global_load_dwordx2 v[136:137], v[214:215], off offset:96
	global_load_dwordx2 v[138:139], v[214:215], off offset:128
	global_load_dwordx2 v[140:141], v[214:215], off offset:160
	global_load_dwordx2 v[142:143], v[214:215], off offset:192
	global_load_dwordx2 v[144:145], v[214:215], off offset:224
	global_load_dwordx2 v[170:171], v[214:215], off offset:256
	global_load_dwordx2 v[172:173], v[214:215], off offset:288
	global_load_dwordx2 v[174:175], v[214:215], off offset:320
	global_load_dwordx2 v[176:177], v[214:215], off offset:352
	global_load_dwordx2 v[178:179], v[214:215], off offset:384
	global_load_dwordx2 v[180:181], v[214:215], off offset:416
	global_load_dwordx2 v[182:183], v[214:215], off offset:448
	global_load_dwordx2 v[184:185], v[214:215], off offset:480
	v_max_f32_e32 v122, v208, v208
	v_max_f32_e32 v122, 0xda24260, v122
	v_div_scale_f32 v123, s[0:1], v122, v122, 1.0
	v_rcp_f32_e32 v124, v123
	s_nop 0
	v_fma_f32 v125, -v123, v124, 1.0
	v_fmac_f32_e32 v124, v125, v124
	v_div_scale_f32 v125, vcc, 1.0, v122, 1.0
	v_mul_f32_e32 v127, v125, v124
	v_fma_f32 v128, -v123, v127, v125
	v_fmac_f32_e32 v127, v128, v124
	v_fma_f32 v123, -v123, v127, v125
	v_div_fmas_f32 v123, v123, v124, v127
	v_div_fixup_f32 v129, v123, v122, 1.0
	s_waitcnt vmcnt(0)
; __device__ __forceinline__ unsigned cvt_pk_bf16(float lo, float hi) { unsigned r; asm("v_cvt_pk_bf16_f32 %0, %1, %2" : "=v"(r) : "v"(lo), "v"(hi)); return r; }
; __device__ __forceinline__ float bflo(unsigned w) { return __uint_as_float(w << 16); }
; __device__ __forceinline__ float bfhi(unsigned w) { return __uint_as_float(w & 0xffff0000u); }
; __device__ __forceinline__ void memattn_unit(LAS unsigned char* lds, const Ctx& P, int unit) {
;     ...
;     const float inv = 1.0f / fmaxf(lsum, 1e-30f);
; #pragma unroll
;     for (int dt = 0; dt < 16; ++dt) { const int d0 = 16 * dt + 4 * i; const u32x2 g = *(const u32x2*)(H + tok * LDH + C_GM + head * 256 + d0);
;         u32x2 w; w.x = cvt_pk_bf16(o[dt][0] * inv * bflo(g.x), o[dt][1] * inv * bfhi(g.x)); w.y = cvt_pk_bf16(o[dt][2] * inv * bflo(g.y), o[dt][3] * inv * bfhi(g.y));
;         *(u32x2*)(O + tok * DBR + head * 256 + d0) = w; }
	s_nop 7
	v_lshlrev_b32_e32 v122, 16, v130
	v_and_b32_e32 v123, 0xffff0000, v130
	v_mul_f32_e32 v124, v34, v129
	v_mul_f32_e32 v125, v35, v129
	v_mul_f32_e32 v124, v124, v122
	v_mul_f32_e32 v125, v125, v123
	v_cvt_pk_bf16_f32 v222, v124, v125
	v_lshlrev_b32_e32 v122, 16, v131
	v_and_b32_e32 v123, 0xffff0000, v131
	v_mul_f32_e32 v124, v36, v129
	v_mul_f32_e32 v125, v37, v129
	v_mul_f32_e32 v124, v124, v122
	v_mul_f32_e32 v125, v125, v123
	v_cvt_pk_bf16_f32 v223, v124, v125
	global_store_dwordx2 v221, v[222:223], s[4:5]
	v_lshlrev_b32_e32 v122, 16, v132
	v_and_b32_e32 v123, 0xffff0000, v132
	v_mul_f32_e32 v124, v38, v129
	v_mul_f32_e32 v125, v39, v129
	v_mul_f32_e32 v124, v124, v122
	v_mul_f32_e32 v125, v125, v123
	v_cvt_pk_bf16_f32 v222, v124, v125
	v_lshlrev_b32_e32 v122, 16, v133
	v_and_b32_e32 v123, 0xffff0000, v133
	v_mul_f32_e32 v124, v40, v129
	v_mul_f32_e32 v125, v41, v129
	v_mul_f32_e32 v124, v124, v122
	v_mul_f32_e32 v125, v125, v123
	v_cvt_pk_bf16_f32 v223, v124, v125
	global_store_dwordx2 v221, v[222:223], s[4:5] offset:32
	v_lshlrev_b32_e32 v122, 16, v134
	v_and_b32_e32 v123, 0xffff0000, v134
	v_mul_f32_e32 v124, v42, v129
	v_mul_f32_e32 v125, v43, v129
	v_mul_f32_e32 v124, v124, v122
	v_mul_f32_e32 v125, v125, v123
	v_cvt_pk_bf16_f32 v222, v124, v125
	v_lshlrev_b32_e32 v122, 16, v135
	v_and_b32_e32 v123, 0xffff0000, v135
	v_mul_f32_e32 v124, v44, v129
	v_mul_f32_e32 v125, v45, v129
	v_mul_f32_e32 v124, v124, v122
	v_mul_f32_e32 v125, v125, v123
	v_cvt_pk_bf16_f32 v223, v124, v125
	global_store_dwordx2 v221, v[222:223], s[4:5] offset:64
	v_lshlrev_b32_e32 v122, 16, v136
	v_and_b32_e32 v123, 0xffff0000, v136
	v_mul_f32_e32 v124, v46, v129
	v_mul_f32_e32 v125, v47, v129
	v_mul_f32_e32 v124, v124, v122
	v_mul_f32_e32 v125, v125, v123
	v_cvt_pk_bf16_f32 v222, v124, v125
	v_lshlrev_b32_e32 v122, 16, v137
	v_and_b32_e32 v123, 0xffff0000, v137
	v_mul_f32_e32 v124, v48, v129
	v_mul_f32_e32 v125, v49, v129
	v_mul_f32_e32 v124, v124, v122
	v_mul_f32_e32 v125, v125, v123
	v_cvt_pk_bf16_f32 v223, v124, v125
	global_store_dwordx2 v221, v[222:223], s[4:5] offset:96
	v_lshlrev_b32_e32 v122, 16, v138
	v_and_b32_e32 v123, 0xffff0000, v138
	v_mul_f32_e32 v124, v50, v129
	v_mul_f32_e32 v125, v51, v129
	v_mul_f32_e32 v124, v124, v122
	v_mul_f32_e32 v125, v125, v123
	v_cvt_pk_bf16_f32 v222, v124, v125
	v_lshlrev_b32_e32 v122, 16, v139
	v_and_b32_e32 v123, 0xffff0000, v139
	v_mul_f32_e32 v124, v52, v129
	v_mul_f32_e32 v125, v53, v129
	v_mul_f32_e32 v124, v124, v122
	v_mul_f32_e32 v125, v125, v123
	v_cvt_pk_bf16_f32 v223, v124, v125
	global_store_dwordx2 v221, v[222:223], s[4:5] offset:128
	v_lshlrev_b32_e32 v122, 16, v140
	v_and_b32_e32 v123, 0xffff0000, v140
	v_mul_f32_e32 v124, v54, v129
	v_mul_f32_e32 v125, v55, v129
	v_mul_f32_e32 v124, v124, v122
	v_mul_f32_e32 v125, v125, v123
	v_cvt_pk_bf16_f32 v222, v124, v125
	v_lshlrev_b32_e32 v122, 16, v141
	v_and_b32_e32 v123, 0xffff0000, v141
	v_mul_f32_e32 v124, v56, v129
	v_mul_f32_e32 v125, v57, v129
	v_mul_f32_e32 v124, v124, v122
	v_mul_f32_e32 v125, v125, v123
	v_cvt_pk_bf16_f32 v223, v124, v125
	global_store_dwordx2 v221, v[222:223], s[4:5] offset:160
	v_lshlrev_b32_e32 v122, 16, v142
	v_and_b32_e32 v123, 0xffff0000, v142
	v_mul_f32_e32 v124, v58, v129
	v_mul_f32_e32 v125, v59, v129
	v_mul_f32_e32 v124, v124, v122
	v_mul_f32_e32 v125, v125, v123
	v_cvt_pk_bf16_f32 v222, v124, v125
	v_lshlrev_b32_e32 v122, 16, v143
	v_and_b32_e32 v123, 0xffff0000, v143
	v_mul_f32_e32 v124, v60, v129
	v_mul_f32_e32 v125, v61, v129
	v_mul_f32_e32 v124, v124, v122
	v_mul_f32_e32 v125, v125, v123
	v_cvt_pk_bf16_f32 v223, v124, v125
	global_store_dwordx2 v221, v[222:223], s[4:5] offset:192
	v_lshlrev_b32_e32 v122, 16, v144
	v_and_b32_e32 v123, 0xffff0000, v144
	v_mul_f32_e32 v124, v62, v129
	v_mul_f32_e32 v125, v63, v129
	v_mul_f32_e32 v124, v124, v122
	v_mul_f32_e32 v125, v125, v123
	v_cvt_pk_bf16_f32 v222, v124, v125
	v_lshlrev_b32_e32 v122, 16, v145
	v_and_b32_e32 v123, 0xffff0000, v145
	v_mul_f32_e32 v124, v64, v129
	v_mul_f32_e32 v125, v65, v129
	v_mul_f32_e32 v124, v124, v122
	v_mul_f32_e32 v125, v125, v123
	v_cvt_pk_bf16_f32 v223, v124, v125
	global_store_dwordx2 v221, v[222:223], s[4:5] offset:224
	v_lshlrev_b32_e32 v122, 16, v170
	v_and_b32_e32 v123, 0xffff0000, v170
; __device__ __forceinline__ unsigned cvt_pk_bf16(float lo, float hi) { unsigned r; asm("v_cvt_pk_bf16_f32 %0, %1, %2" : "=v"(r) : "v"(lo), "v"(hi)); return r; }
; __device__ __forceinline__ float bflo(unsigned w) { return __uint_as_float(w << 16); }
; __device__ __forceinline__ float bfhi(unsigned w) { return __uint_as_float(w & 0xffff0000u); }
; __device__ __forceinline__ void memattn_unit(LAS unsigned char* lds, const Ctx& P, int unit) {
;     ...
;     for (int dt = 0; dt < 16; ++dt) { const int d0 = 16 * dt + 4 * i; const u32x2 g = *(const u32x2*)(H + tok * LDH + C_GM + head * 256 + d0);
;         u32x2 w; w.x = cvt_pk_bf16(o[dt][0] * inv * bflo(g.x), o[dt][1] * inv * bfhi(g.x)); w.y = cvt_pk_bf16(o[dt][2] * inv * bflo(g.y), o[dt][3] * inv * bfhi(g.y));
;         *(u32x2*)(O + tok * DBR + head * 256 + d0) = w; }
; __global__ void __launch_bounds__(512, 2) fwd_megakernel(Params PK) {
;     ...
;             for (int u = bid; u < 512; u += G) memattn_unit(lds, P, u);
	v_mul_f32_e32 v124, v66, v129
	v_mul_f32_e32 v125, v67, v129
	v_mul_f32_e32 v124, v124, v122
	v_mul_f32_e32 v125, v125, v123
	v_cvt_pk_bf16_f32 v222, v124, v125
	v_lshlrev_b32_e32 v122, 16, v171
	v_and_b32_e32 v123, 0xffff0000, v171
	v_mul_f32_e32 v124, v68, v129
	v_mul_f32_e32 v125, v69, v129
	v_mul_f32_e32 v124, v124, v122
	v_mul_f32_e32 v125, v125, v123
	v_cvt_pk_bf16_f32 v223, v124, v125
	global_store_dwordx2 v221, v[222:223], s[4:5] offset:256
	v_lshlrev_b32_e32 v122, 16, v172
	v_and_b32_e32 v123, 0xffff0000, v172
	v_mul_f32_e32 v124, v70, v129
	v_mul_f32_e32 v125, v71, v129
	v_mul_f32_e32 v124, v124, v122
	v_mul_f32_e32 v125, v125, v123
	v_cvt_pk_bf16_f32 v222, v124, v125
	v_lshlrev_b32_e32 v122, 16, v173
	v_and_b32_e32 v123, 0xffff0000, v173
	v_mul_f32_e32 v124, v72, v129
	v_mul_f32_e32 v125, v73, v129
	v_mul_f32_e32 v124, v124, v122
	v_mul_f32_e32 v125, v125, v123
	v_cvt_pk_bf16_f32 v223, v124, v125
	global_store_dwordx2 v221, v[222:223], s[4:5] offset:288
	v_lshlrev_b32_e32 v122, 16, v174
	v_and_b32_e32 v123, 0xffff0000, v174
	v_mul_f32_e32 v124, v74, v129
	v_mul_f32_e32 v125, v75, v129
	v_mul_f32_e32 v124, v124, v122
	v_mul_f32_e32 v125, v125, v123
	v_cvt_pk_bf16_f32 v222, v124, v125
	v_lshlrev_b32_e32 v122, 16, v175
	v_and_b32_e32 v123, 0xffff0000, v175
	v_mul_f32_e32 v124, v76, v129
	v_mul_f32_e32 v125, v77, v129
	v_mul_f32_e32 v124, v124, v122
	v_mul_f32_e32 v125, v125, v123
	v_cvt_pk_bf16_f32 v223, v124, v125
	global_store_dwordx2 v221, v[222:223], s[4:5] offset:320
	v_lshlrev_b32_e32 v122, 16, v176
	v_and_b32_e32 v123, 0xffff0000, v176
	v_mul_f32_e32 v124, v78, v129
	v_mul_f32_e32 v125, v79, v129
	v_mul_f32_e32 v124, v124, v122
	v_mul_f32_e32 v125, v125, v123
	v_cvt_pk_bf16_f32 v222, v124, v125
	v_lshlrev_b32_e32 v122, 16, v177
	v_and_b32_e32 v123, 0xffff0000, v177
	v_mul_f32_e32 v124, v80, v129
	v_mul_f32_e32 v125, v81, v129
	v_mul_f32_e32 v124, v124, v122
	v_mul_f32_e32 v125, v125, v123
	v_cvt_pk_bf16_f32 v223, v124, v125
	global_store_dwordx2 v221, v[222:223], s[4:5] offset:352
	v_lshlrev_b32_e32 v122, 16, v178
	v_and_b32_e32 v123, 0xffff0000, v178
	v_mul_f32_e32 v124, v82, v129
	v_mul_f32_e32 v125, v83, v129
	v_mul_f32_e32 v124, v124, v122
	v_mul_f32_e32 v125, v125, v123
	v_cvt_pk_bf16_f32 v222, v124, v125
	v_lshlrev_b32_e32 v122, 16, v179
	v_and_b32_e32 v123, 0xffff0000, v179
	v_mul_f32_e32 v124, v84, v129
	v_mul_f32_e32 v125, v85, v129
	v_mul_f32_e32 v124, v124, v122
	v_mul_f32_e32 v125, v125, v123
	v_cvt_pk_bf16_f32 v223, v124, v125
	global_store_dwordx2 v221, v[222:223], s[4:5] offset:384
	v_lshlrev_b32_e32 v122, 16, v180
	v_and_b32_e32 v123, 0xffff0000, v180
	v_mul_f32_e32 v124, v86, v129
	v_mul_f32_e32 v125, v87, v129
	v_mul_f32_e32 v124, v124, v122
	v_mul_f32_e32 v125, v125, v123
	v_cvt_pk_bf16_f32 v222, v124, v125
	v_lshlrev_b32_e32 v122, 16, v181
	v_and_b32_e32 v123, 0xffff0000, v181
	v_mul_f32_e32 v124, v88, v129
	v_mul_f32_e32 v125, v89, v129
	v_mul_f32_e32 v124, v124, v122
	v_mul_f32_e32 v125, v125, v123
	v_cvt_pk_bf16_f32 v223, v124, v125
	global_store_dwordx2 v221, v[222:223], s[4:5] offset:416
	v_lshlrev_b32_e32 v122, 16, v182
	v_and_b32_e32 v123, 0xffff0000, v182
	v_mul_f32_e32 v124, v90, v129
	v_mul_f32_e32 v125, v91, v129
	v_mul_f32_e32 v124, v124, v122
	v_mul_f32_e32 v125, v125, v123
	v_cvt_pk_bf16_f32 v222, v124, v125
	v_lshlrev_b32_e32 v122, 16, v183
	v_and_b32_e32 v123, 0xffff0000, v183
	v_mul_f32_e32 v124, v92, v129
	v_mul_f32_e32 v125, v93, v129
	v_mul_f32_e32 v124, v124, v122
	v_mul_f32_e32 v125, v125, v123
	v_cvt_pk_bf16_f32 v223, v124, v125
	global_store_dwordx2 v221, v[222:223], s[4:5] offset:448
	v_lshlrev_b32_e32 v122, 16, v184
	v_and_b32_e32 v123, 0xffff0000, v184
	v_mul_f32_e32 v124, v94, v129
	v_mul_f32_e32 v125, v95, v129
	v_mul_f32_e32 v124, v124, v122
	v_mul_f32_e32 v125, v125, v123
	v_cvt_pk_bf16_f32 v222, v124, v125
	v_lshlrev_b32_e32 v122, 16, v185
	v_and_b32_e32 v123, 0xffff0000, v185
	v_mul_f32_e32 v124, v96, v129
	v_mul_f32_e32 v125, v97, v129
	v_mul_f32_e32 v124, v124, v122
	v_mul_f32_e32 v125, v125, v123
	v_cvt_pk_bf16_f32 v223, v124, v125
	global_store_dwordx2 v221, v[222:223], s[4:5] offset:480
	s_add_u32 s7, s7, s34
	s_branch .Lmem_unit
.Lmem_done:
	s_branch .Lp2_disp
.LBB0_859:
	s_mov_b64 s[0:1], 0
	v_readlane_b32 s44, v255, 47
